# barrier before MLP1 made split-phase: XCD leaders arrive (flush + count) and release their own XCD at once; each wave checks the global generation only before its first MLP1 stores of the phase
# speedup vs baseline: 1.0251x; 1.0043x over previous
; DEVI void phase7(const Params& p, int l, char* lds) {
;     ...
;   for (int it = 0; have; ++it) {
;     int mt2 = 0, nt2 = 0;
;     const bool have2 = tile_map(it + 1, 16, mt2, nt2);
;     const int m0 = mt * 256, n0 = nt * 256;
;     const GUnit cur{hn + (long)m0 * LDX, wT + (long)n0 * LDX, LDX, LDX, 16};
;     const GUnit nxt{hn + (long)mt2 * 256 * LDX, wT + (long)nt2 * 256 * LDX, LDX, LDX, 16};
;     const float* rsS = stage_rstd((const float*)(p.ws + OFF_SSQB), m0, it, lds);
;     f32x4 acc[4][8];
;     zero_acc8(acc);
;     gemm16s(acc, cur, nxt, have2, it == 0, stg, (bfu*)lds);
;     mt = mt2; nt = nt2; have = have2;
;     float rs8[8];
; #pragma unroll
;     for (int mi = 0; mi < 8; ++mi) rs8[mi] = rsS[wm * 128 + mi * 16 + fr];
; #pragma unroll
;     for (int ni = 0; ni < 4; ++ni)
; #pragma unroll
;       for (int mi = 0; mi < 8; ++mi) {
;         f32x4 v = acc[ni][mi];
; #pragma unroll
;         for (int j = 0; j < 4; ++j) { float r = fmaxf(v[j] * rs8[mi], 0.f); v[j] = r * r; }
;         int n = n0 + wn * 64 + ni * 16 + fq * 4;
;         int m = m0 + wm * 128 + mi * 16 + fr;
;         store_bf4(hid + (long)m * LDH + n, v);
.LBB0_204:
	s_cmp_eq_u32 s100, 0
	s_cbranch_scc1 .Lp7_released
	v_readlane_b32 vcc_lo, v242, 28
	v_readlane_b32 vcc_hi, v242, 29
.Lp7_poll:
	s_nop 4
	global_load_dword v0, v1, vcc sc1
	s_waitcnt vmcnt(0)
	v_readfirstlane_b32 s101, v0
	s_cmp_ge_u32 s101, s100
	s_cbranch_scc1 .Lp7_ok
	s_sleep 1
	s_branch .Lp7_poll
.Lp7_ok:
	s_mov_b32 s100, 0

; __global__ void __launch_bounds__(512, 2) fwd_mega(Params p, int ph_lo, int ph_hi, int coop) {
;     ...
;   for (int ph = ph_lo; ph < ph_hi; ++ph) {
;     run_phase(p, ph, lds, nsa_cnt_s, p4_stage, false);
;     ...
;     if ((REP_MASK >> (ph % PH_PER_LAYER)) & 1) { xcd_barrier(xb); run_phase(p, ph, lds, nsa_cnt_s, p4_stage, true); }
;     ...
;     for (int e = 0; e < EXTRA_SYNCS; ++e) xcd_barrier(xb);
;     ...
;     if (coop && ph + 1 < ph_hi) {
;       if (coop & 2) cg::this_grid().sync();
;       else xcd_barrier(xb);
;     }
.LBB0_915:
	s_add_i32 s92, s92, 1
	s_and_b32 s100, s92, 7
	s_lshr_b32 s101, s92, 3
	s_mul_i32 s101, s101, 3
	s_add_i32 s101, s101, 2
	s_cmp_eq_u32 s100, 6
	s_cselect_b32 s100, s101, 0
	s_cmp_ge_i32 s92, s93
	s_cselect_b64 s[0:1], -1, 0
	s_cmp_lt_i32 s92, s93
	s_waitcnt lgkmcnt(0)
	v_readlane_b32 s26, v244, 1
	s_cselect_b64 s[4:5], -1, 0
	v_readlane_b32 s27, v244, 2
	s_and_b64 s[4:5], s[26:27], s[4:5]
	s_andn2_b64 vcc, exec, s[4:5]
	s_cbranch_vccz .LBB0_916
	s_getpc_b64 s[98:99]

; DEVI unsigned xb_ld(unsigned* p) { return __hip_atomic_load(p, __ATOMIC_RELAXED, __HIP_MEMORY_SCOPE_AGENT); }
; DEVI unsigned xb_add(unsigned* p, unsigned v) { return __hip_atomic_fetch_add(p, v, __ATOMIC_RELAXED, __HIP_MEMORY_SCOPE_AGENT); }
; #define XB_SPIN(cond, bar) do { unsigned _sp = 0; while (cond) { __builtin_amdgcn_s_sleep(1); \
;     if ((++_sp & 255u) == 0u) { if (xb_ld(&(bar)[XB_TMO])) break; if (_sp > XB_SPIN_CAP) { atomicAdd(&(bar)[XB_TMO], 1u); break; } } } } while (0)
; DEVI void xcd_barrier(const XcdBarrier& b) {
;     ...
;     const unsigned old = xb_add(&bar[XB_XSUB(b.x)], 1u);
;     const unsigned gen = old / nloc;
;     if (old + 1u == (gen + 1u) * nloc) {
;       __builtin_amdgcn_fence(__ATOMIC_RELEASE, "agent");
;       asm volatile("s_waitcnt vmcnt(0)" ::: "memory");
;       const unsigned og = xb_add(&bar[XB_TOP], 1u);
;       const unsigned tg = og / nx;
;       if (og + 1u == (tg + 1u) * nx) xb_add(&bar[XB_TOPGEN], 1u);
;       else XB_SPIN(xb_ld(&bar[XB_TOPGEN]) == tg, bar);
.LBB0_962:
	s_mov_b32 s101, 0
	s_and_b32 s20, s92, 7
	s_cmp_lt_u32 s20, 2
	s_cbranch_scc1 .Lxb_global
	v_readfirstlane_b32 s20, v246
	s_bcnt1_i32_b32 s20, s20
	s_cmp_lg_u32 s20, 1
	s_cbranch_scc1 .Lxb_global
	v_readfirstlane_b32 s20, v247
	s_bcnt1_i32_b32 s20, s20
	s_cmp_lg_u32 s20, 1
	s_cbranch_scc1 .Lxb_global
	v_readfirstlane_b32 s20, v248
	s_bcnt1_i32_b32 s20, s20
	s_cmp_lg_u32 s20, 1
	s_cbranch_scc1 .Lxb_global
	v_readfirstlane_b32 s20, v249
	s_bcnt1_i32_b32 s20, s20
	s_cmp_lg_u32 s20, 1
	s_cbranch_scc1 .Lxb_global
	v_readfirstlane_b32 s20, v250
	s_bcnt1_i32_b32 s20, s20
	s_cmp_lg_u32 s20, 1
	s_cbranch_scc1 .Lxb_global
	v_readfirstlane_b32 s20, v251
	s_bcnt1_i32_b32 s20, s20
	s_cmp_lg_u32 s20, 1
	s_cbranch_scc1 .Lxb_global
	v_readfirstlane_b32 s20, v252
	s_bcnt1_i32_b32 s20, s20
	s_cmp_lg_u32 s20, 1
	s_cbranch_scc1 .Lxb_global
	v_readfirstlane_b32 s20, v253
	s_bcnt1_i32_b32 s20, s20
	s_cmp_lg_u32 s20, 1
	s_cbranch_scc1 .Lxb_global
	s_and_b32 s20, s92, 7
	s_cmp_eq_u32 s20, 6
	s_cbranch_scc0 .Lxb_local_leader
	s_mov_b32 s101, 1

; DEVI unsigned xb_ld(unsigned* p) { return __hip_atomic_load(p, __ATOMIC_RELAXED, __HIP_MEMORY_SCOPE_AGENT); }
; DEVI unsigned xb_add(unsigned* p, unsigned v) { return __hip_atomic_fetch_add(p, v, __ATOMIC_RELAXED, __HIP_MEMORY_SCOPE_AGENT); }
; #define XB_SPIN(cond, bar) do { unsigned _sp = 0; while (cond) { __builtin_amdgcn_s_sleep(1); \
;     if ((++_sp & 255u) == 0u) { if (xb_ld(&(bar)[XB_TMO])) break; if (_sp > XB_SPIN_CAP) { atomicAdd(&(bar)[XB_TMO], 1u); break; } } } } while (0)
; DEVI void xcd_barrier(const XcdBarrier& b) {
;     ...
;       const unsigned og = xb_add(&bar[XB_TOP], 1u);
;       const unsigned tg = og / nx;
;       if (og + 1u == (tg + 1u) * nx) xb_add(&bar[XB_TOPGEN], 1u);
;       else XB_SPIN(xb_ld(&bar[XB_TOPGEN]) == tg, bar);
.LBB0_964:
	s_or_b64 exec, exec, s[38:39]
	s_waitcnt vmcnt(0)
	v_readfirstlane_b32 s20, v3
	v_sub_u32_e32 v4, 0, v2
	s_mov_b64 s[38:39], -1
	v_add_u32_e32 v3, s20, v0
	v_cvt_f32_u32_e32 v0, v2
	v_readlane_b32 s20, v242, 28
	v_readlane_b32 s21, v242, 29
	v_rcp_iflag_f32_e32 v0, v0
	s_nop 0
	v_mul_f32_e32 v0, 0x4f7ffffe, v0
	v_cvt_u32_f32_e32 v0, v0
	v_mul_lo_u32 v4, v4, v0
	v_mul_hi_u32 v4, v0, v4
	v_add_u32_e32 v0, v0, v4
	v_mul_hi_u32 v0, v3, v0
	v_mul_lo_u32 v4, v0, v2
	v_sub_u32_e32 v4, v3, v4
	v_cmp_ge_u32_e32 vcc, v4, v2
	v_add_u32_e32 v5, 1, v0
	v_add_u32_e32 v3, 1, v3
	v_cndmask_b32_e32 v0, v0, v5, vcc
	v_sub_u32_e32 v5, v4, v2
	v_cndmask_b32_e32 v4, v4, v5, vcc
	v_cmp_ge_u32_e32 vcc, v4, v2
	v_add_u32_e32 v4, 1, v0
	s_nop 0
	v_cndmask_b32_e32 v0, v0, v4, vcc
	v_mul_lo_u32 v4, v2, v0
	v_add_u32_e32 v2, v4, v2
	v_cmp_ne_u32_e32 vcc, v3, v2
	v_mov_b64_e32 v[2:3], s[20:21]
	s_and_saveexec_b64 s[36:37], vcc
	s_cbranch_execz .LBB0_976
	s_cmp_eq_u32 s101, 1
	s_cbranch_scc0 .Lxb_spin
	s_mov_b64 s[38:39], 0
	s_branch .LBB0_976
.Lxb_spin:
	v_readlane_b32 s20, v242, 28
	v_readlane_b32 s21, v242, 29
	s_mov_b64 s[40:41], 0
	s_nop 3
	global_load_dword v2, v1, s[20:21] sc1
	s_waitcnt vmcnt(0)
	v_cmp_eq_u32_e32 vcc, v2, v0
	s_and_saveexec_b64 s[38:39], vcc
	s_cbranch_execz .LBB0_975
	s_mov_b32 s20, 1
	s_branch .LBB0_968

; __global__ void __launch_bounds__(512, 2) fwd_mega(Params p, int ph_lo, int ph_hi, int coop) {
;   extern __shared__ __attribute__((aligned(16))) char lds[];
	.amdhsa_kernel _Z8fwd_mega6Paramsiii
		.amdhsa_group_segment_fixed_size 3104
		.amdhsa_private_segment_fixed_size 0
		.amdhsa_kernarg_size 480
		.amdhsa_user_sgpr_count 2
		.amdhsa_user_sgpr_dispatch_ptr 0
		.amdhsa_user_sgpr_queue_ptr 0
		.amdhsa_user_sgpr_kernarg_segment_ptr 1
		.amdhsa_user_sgpr_dispatch_id 0
		.amdhsa_user_sgpr_kernarg_preload_length 0
		.amdhsa_user_sgpr_kernarg_preload_offset 0
		.amdhsa_user_sgpr_private_segment_size 0
		.amdhsa_uses_dynamic_stack 0
		.amdhsa_enable_private_segment 0
		.amdhsa_system_sgpr_workgroup_id_x 1
		.amdhsa_system_sgpr_workgroup_id_y 0
		.amdhsa_system_sgpr_workgroup_id_z 0
		.amdhsa_system_sgpr_workgroup_info 0
		.amdhsa_system_vgpr_workitem_id 2
		.amdhsa_next_free_vgpr 256
		.amdhsa_next_free_sgpr 102
		.amdhsa_accum_offset 256
		.amdhsa_reserve_vcc 1
		.amdhsa_float_round_mode_32 0
		.amdhsa_float_round_mode_16_64 0
		.amdhsa_float_denorm_mode_32 3
		.amdhsa_float_denorm_mode_16_64 3
		.amdhsa_dx10_clamp 1
		.amdhsa_ieee_mode 1
		.amdhsa_fp16_overflow 0
		.amdhsa_tg_split 0
		.amdhsa_exception_fp_ieee_invalid_op 0
		.amdhsa_exception_fp_denorm_src 0
		.amdhsa_exception_fp_ieee_div_zero 0
		.amdhsa_exception_fp_ieee_overflow 0
		.amdhsa_exception_fp_ieee_underflow 0
		.amdhsa_exception_fp_ieee_inexact 0
		.amdhsa_exception_int_div_zero 0
	.end_amdhsa_kernel

; __global__ void __launch_bounds__(512, 2) fwd_mega(Params p, int ph_lo, int ph_hi, int coop) {
;   extern __shared__ __attribute__((aligned(16))) char lds[];
amdhsa.kernels:
  - .agpr_count:     0
    .args:
      - .offset:         0
        .size:           208
        .value_kind:     by_value
      - .offset:         208
        .size:           4
        .value_kind:     by_value
      - .offset:         212
        .size:           4
        .value_kind:     by_value
      - .offset:         216
        .size:           4
        .value_kind:     by_value
      - .offset:         224
        .size:           4
        .value_kind:     hidden_block_count_x
      - .offset:         228
        .size:           4
        .value_kind:     hidden_block_count_y
      - .offset:         232
        .size:           4
        .value_kind:     hidden_block_count_z
      - .offset:         236
        .size:           2
        .value_kind:     hidden_group_size_x
      - .offset:         238
        .size:           2
        .value_kind:     hidden_group_size_y
      - .offset:         240
        .size:           2
        .value_kind:     hidden_group_size_z
      - .offset:         242
        .size:           2
        .value_kind:     hidden_remainder_x
      - .offset:         244
        .size:           2
        .value_kind:     hidden_remainder_y
      - .offset:         246
        .size:           2
        .value_kind:     hidden_remainder_z
      - .offset:         264
        .size:           8
        .value_kind:     hidden_global_offset_x
      - .offset:         272
        .size:           8
        .value_kind:     hidden_global_offset_y
      - .offset:         280
        .size:           8
        .value_kind:     hidden_global_offset_z
      - .offset:         288
        .size:           2
        .value_kind:     hidden_grid_dims
      - .offset:         312
        .size:           8
        .value_kind:     hidden_multigrid_sync_arg
      - .offset:         344
        .size:           4
        .value_kind:     hidden_dynamic_lds_size
    .group_segment_fixed_size: 3104
    .kernarg_segment_align: 8
    .kernarg_segment_size: 480
    .language:       OpenCL C
    .language_version:
      - 2
      - 0
    .max_flat_workgroup_size: 512
    .name:           _Z8fwd_mega6Paramsiii
    .private_segment_fixed_size: 0
    .sgpr_count:     108
    .sgpr_spill_count: 189
    .symbol:         _Z8fwd_mega6Paramsiii.kd
    .uniform_work_group_size: 1
    .uses_dynamic_stack: false
    .vgpr_count:     256
    .vgpr_spill_count: 0
    .wavefront_size: 64
